# grid barrier: all workgroups poll the top counter directly (drops the XGEN/TOPGEN relay legs)
# speedup vs baseline: 1.0059x; 1.0043x over previous
.LBB0_555:
	s_waitcnt lgkmcnt(0)
	v_readlane_b32 s10, v253, 59
	v_readlane_b32 s11, v253, 60
	v_mov_b32_e32 v3, 1
	v_cvt_f32_u32_e32 v4, v2
	s_nop 4
	global_atomic_add v3, v17, v3, s[10:11] sc0
	v_rcp_f32_e32 v4, v4
	s_waitcnt vmcnt(0)
	v_cvt_f32_u32_e32 v5, v3
	v_add_f32_e32 v5, 0.5, v5
	v_mul_f32_e32 v5, v5, v4
	v_cvt_u32_f32_e32 v1, v5
	v_add_u32_e32 v6, 1, v1
	v_mul_lo_u32 v4, v6, v2
	v_add_u32_e32 v5, 1, v3
	v_mul_lo_u32 v0, v6, v0
	v_cmp_eq_u32_e32 vcc, v5, v4
	s_cbranch_vccz .Lxb0_wait
	buffer_wbl2 sc1
	s_waitcnt vmcnt(0)
	v_readlane_b32 s10, v253, 63
	v_readlane_b32 s11, v254, 0
	v_mov_b32_e32 v3, 1
	s_nop 4
	global_atomic_add v17, v3, s[10:11]
.Lxb0_wait:
	v_readlane_b32 s10, v253, 63
	v_readlane_b32 s11, v254, 0
	s_mov_b32 s8, 0
	s_nop 4
.Lxb0_spin:
	global_load_dword v3, v17, s[10:11] sc1
	s_waitcnt vmcnt(0)
	v_sub_u32_e32 v3, v3, v0
	v_cmp_gt_i32_e32 vcc, 0, v3
	s_cbranch_vccz .Lxb0_rel
	s_sleep 1
	s_add_i32 s8, s8, 1
	s_cmp_lt_u32 s8, 0x8000
	s_cbranch_scc1 .Lxb0_spin
.Lxb0_rel:
	buffer_inv sc1
	s_waitcnt vmcnt(0)
	v_readlane_b32 s34, v254, 46
	v_readlane_b32 s35, v254, 47

.LBB0_612:
	s_waitcnt lgkmcnt(0)
	v_readlane_b32 s8, v253, 59
	v_readlane_b32 s9, v253, 60
	v_mov_b32_e32 v3, 1
	v_cvt_f32_u32_e32 v4, v2
	s_nop 4
	global_atomic_add v3, v17, v3, s[8:9] sc0
	v_rcp_f32_e32 v4, v4
	s_waitcnt vmcnt(0)
	v_cvt_f32_u32_e32 v5, v3
	v_add_f32_e32 v5, 0.5, v5
	v_mul_f32_e32 v5, v5, v4
	v_cvt_u32_f32_e32 v1, v5
	v_add_u32_e32 v6, 1, v1
	v_mul_lo_u32 v4, v6, v2
	v_add_u32_e32 v5, 1, v3
	v_mul_lo_u32 v0, v6, v0
	v_cmp_eq_u32_e32 vcc, v5, v4
	s_cbranch_vccz .Lxb1_wait
	buffer_wbl2 sc1
	s_waitcnt vmcnt(0)
	v_readlane_b32 s8, v253, 63
	v_readlane_b32 s9, v254, 0
	v_mov_b32_e32 v3, 1
	s_nop 4
	global_atomic_add v17, v3, s[8:9]
.Lxb1_wait:
	v_readlane_b32 s8, v253, 63
	v_readlane_b32 s9, v254, 0
	s_mov_b32 s6, 0
	s_nop 4
.Lxb1_spin:
	global_load_dword v3, v17, s[8:9] sc1
	s_waitcnt vmcnt(0)
	v_sub_u32_e32 v3, v3, v0
	v_cmp_gt_i32_e32 vcc, 0, v3
	s_cbranch_vccz .Lxb1_rel
	s_sleep 1
	s_add_i32 s6, s6, 1
	s_cmp_lt_u32 s6, 0x8000
	s_cbranch_scc1 .Lxb1_spin
.Lxb1_rel:
	buffer_inv sc1
	s_waitcnt vmcnt(0)

.Lxb2_rel:
	buffer_inv sc1
	s_waitcnt vmcnt(0)
	s_mov_b32 s34, 0x15000
	s_mov_b32 s35, 0x1f000

.LBB0_911:
	s_waitcnt lgkmcnt(0)
	v_readlane_b32 s6, v253, 59
	v_readlane_b32 s7, v253, 60
	v_mov_b32_e32 v3, 1
	v_cvt_f32_u32_e32 v4, v2
	s_nop 4
	global_atomic_add v3, v17, v3, s[6:7] sc0
	v_rcp_f32_e32 v4, v4
	s_waitcnt vmcnt(0)
	v_cvt_f32_u32_e32 v5, v3
	v_add_f32_e32 v5, 0.5, v5
	v_mul_f32_e32 v5, v5, v4
	v_cvt_u32_f32_e32 v1, v5
	v_add_u32_e32 v6, 1, v1
	v_mul_lo_u32 v4, v6, v2
	v_add_u32_e32 v5, 1, v3
	v_mul_lo_u32 v0, v6, v0
	v_cmp_eq_u32_e32 vcc, v5, v4
	s_cbranch_vccz .Lxb3_wait
	buffer_wbl2 sc1
	s_waitcnt vmcnt(0)
	v_readlane_b32 s6, v253, 63
	v_readlane_b32 s7, v254, 0
	v_mov_b32_e32 v3, 1
	s_nop 4
	global_atomic_add v17, v3, s[6:7]
.Lxb3_wait:
	v_readlane_b32 s6, v253, 63
	v_readlane_b32 s7, v254, 0
	s_mov_b32 s4, 0
	s_nop 4
.Lxb3_spin:
	global_load_dword v3, v17, s[6:7] sc1
	s_waitcnt vmcnt(0)
	v_sub_u32_e32 v3, v3, v0
	v_cmp_gt_i32_e32 vcc, 0, v3
	s_cbranch_vccz .Lxb3_rel
	s_sleep 1
	s_add_i32 s4, s4, 1
	s_cmp_lt_u32 s4, 0x8000
	s_cbranch_scc1 .Lxb3_spin

.Lxb7_rel:
	buffer_inv sc1
	s_waitcnt vmcnt(0)
	s_getpc_b64 s[98:99]
